# H + attention: two d-steps of K fragments in flight, first-tile K reads after the pair barrier, ones operand resident in v[128:131], V reads on v157, uniform-branch mask from the compares
# baseline (speedup 1.0000x reference)
; #define LAS __attribute__((address_space(3)))
; __device__ __forceinline__ void attn_unit(const Params& p, LAS unsigned char* lds, int b, int h, int qb, int tid, int wid, int lane, u64& tacc, v4u& kA, v4u& vA, v4u& kB, v4u& vB, const bool first) {
;     const bf16* proj = (const bf16*)(p.ws + WS_PROJ); const u64* bm = (const u64*)((const unsigned char*)p.out + DO_BM); bf16* attn = (bf16*)(p.ws + WS_CA) + 512;
;     const int r32 = lane & 31, hi = lane >> 5;
;     const size_t rowbase = (size_t)b * SEQ; const int q0 = qb * 256;
;     LAS bf16* stg = (LAS bf16*)(lds + 32768) + wid * 2304;
;     const bf16* Qw = proj + (rowbase + q0 + wid * 32) * NPROJ + PC_Q + h * 64;
;     bf16x8 qr[4];
; #pragma unroll
;     for (int d0 = 0; d0 < 4; ++d0) qr[d0] = *(const bf16x8*)(Qw + (size_t)r32 * NPROJ + d0 * 16 + hi * 8);
;     const int NT = 4 * (qb + 1); const int tcw = 4 * qb + (wid >> 1);
;     const bf16* ksrc = (const bf16*)((const unsigned char*)p.out + DO_KBLK) + (size_t)(b * 8 + h) * 64 * 4096 + wid * 512 + lane * 8;
;     const bf16* vsrc = (const bf16*)((const unsigned char*)p.out + DO_VBLK) + (size_t)(b * 8 + h) * 64 * 4096 + wid * 512 + lane * 8;
;     const u64* bmq = bm + (rowbase + q0 + wid * 32 + r32) * 64;
;     const unsigned stoff = wid * 1024 + lane * 16;
;     const unsigned vboff = 8192 + ((lane >> 4) & 1) * 32 + (lane & 3) * 8 + (4 * hi + ((lane & 15) >> 2)) * 64;
; __device__ __forceinline__ void phase4(const Params& p, LAS unsigned char* lds, int vcu, int tid, int wid, int lane) {
;     ...
;     for (int v = vcu; v < 256; v += gridDim.x) {
;         const int bh = v >> 2, s = v & 3;
; #pragma unroll 1
;         for (int i = 0; i < 4; ++i) { const int qb = (i == 0) ? s : (i == 1) ? 7 - s : (i == 2) ? 8 + s : 15 - s; attn_unit(p, lds, bh >> 3, bh & 7, qb, tid, wid, lane, tacc, kA, vA, kB, vB, i == 0); }
.LBB0_3754:
	s_ashr_i32 s0, s85, 5
	s_ashr_i32 s1, s0, 31
	s_and_b32 s38, s85, 3
	s_bfe_u32 s2, s85, 0x30002
	s_lshl_b64 s[4:5], s[0:1], 12
	s_add_u32 s39, s4, s24
	s_addc_u32 s40, s5, 0
	s_lshl_b32 s0, s0, 3
	s_or_b32 s0, s0, s2
	s_ashr_i32 s1, s0, 31
	s_lshl_b64 s[0:1], s[0:1], 19
	s_lshl_b32 s9, s2, 6
	v_lshl_add_u64 v[180:181], v[162:163], 0, s[0:1]
	v_lshl_add_u64 v[182:183], v[164:165], 0, s[0:1]
	s_lshl_b32 s2, s2, 7
	s_or_b32 s41, s38, 8
	s_xor_b32 s42, s38, 15
	s_xor_b32 s43, s38, 7
	v_lshl_add_u64 v[184:185], v[180:181], 0, s[12:13]
	v_lshl_add_u64 v[186:187], v[182:183], 0, s[12:13]
	v_lshl_add_u64 v[188:189], v[180:181], 0, s[14:15]
	v_lshl_add_u64 v[190:191], v[182:183], 0, s[14:15]
	v_lshl_add_u64 v[192:193], v[166:167], 0, s[2:3]
	v_lshl_add_u64 v[194:195], v[168:169], 0, s[4:5]
	s_lshl_b32 s44, s9, 1
	s_mov_b32 s45, s3
	v_mov_b32_e32 v128, s8
	v_mov_b32_e32 v129, s8
	v_mov_b32_e32 v130, s8
	v_mov_b32_e32 v131, s8
	s_branch .LBB0_3756

.LBB0_3761:
	s_add_i32 s0, s51, 2
	s_sub_i32 s1, s0, s48
	s_min_u32 s2, s0, s1
	s_lshl_b64 s[0:1], s[2:3], 13
	v_lshl_add_u64 v[14:15], v[180:181], 0, s[0:1]
	v_lshl_add_u64 v[218:219], v[182:183], 0, s[0:1]
	s_mov_b32 m0, s70
	s_nop 0
	global_load_lds_dwordx4 v[14:15], off
	s_add_i32 m0, s70, 0x2000
	s_nop 0
	global_load_lds_dwordx4 v[218:219], off
	s_add_i32 s0, s51, 3
	s_sub_i32 s1, s0, s48
	s_min_u32 s2, s0, s1
	s_lshl_b64 s[0:1], s[2:3], 13
	v_lshl_add_u64 v[14:15], v[180:181], 0, s[0:1]
	v_lshl_add_u64 v[218:219], v[182:183], 0, s[0:1]
	s_add_i32 m0, s70, 0x4000
	s_nop 0
	global_load_lds_dwordx4 v[14:15], off
	s_add_i32 m0, s70, 0x6000
	s_nop 0
	global_load_lds_dwordx4 v[218:219], off
	s_cmp_gt_u32 s51, s47
	s_cbranch_scc1 .LBB0_3765
	ds_read_b128 v[120:123], v200 offset:2048
	ds_read_b128 v[124:127], v200 offset:2560
	v_lshrrev_b32_e32 v1, v160, v152
	v_lshrrev_b32_e32 v14, v160, v153
	v_bitop3_b32 v228, v1, s27, v1 bitop3:0xc
	v_bitop3_b32 v229, v1, s28, v1 bitop3:0xc
	v_bitop3_b32 v230, v1, s29, v1 bitop3:0xc
	v_bitop3_b32 v231, v1, s30, v1 bitop3:0xc
	s_waitcnt lgkmcnt(3)
	v_mfma_f32_32x32x16_bf16 v[80:95], v[6:9], v[144:147], v[64:79]
	v_mul_u32_u24_e32 v228, 0xf000, v228
	v_mul_u32_u24_e32 v229, 0x7800, v229
	v_mul_u32_u24_e32 v230, 0x3c00, v230
	v_mul_u32_u24_e32 v231, 0x1e00, v231
	s_waitcnt lgkmcnt(2)
	v_mfma_f32_32x32x16_bf16 v[96:111], v[10:13], v[144:147], v[64:79]
	ds_read_b128 v[6:9], v200 offset:4096
	ds_read_b128 v[10:13], v200 offset:4608
	v_bitop3_b32 v232, v14, s27, v14 bitop3:0xc
	v_bitop3_b32 v233, v14, s28, v14 bitop3:0xc
	v_bitop3_b32 v234, v14, s29, v14 bitop3:0xc
	v_bitop3_b32 v235, v14, s30, v14 bitop3:0xc
	v_mul_u32_u24_e32 v232, 0xf000, v232
	v_mul_u32_u24_e32 v233, 0x7800, v233
	v_mul_u32_u24_e32 v234, 0x3c00, v234
	v_mul_u32_u24_e32 v235, 0x1e00, v235
	s_waitcnt lgkmcnt(3)
	v_mfma_f32_32x32x16_bf16 v[80:95], v[120:123], v[136:139], v[80:95]
	v_bitop3_b32 v236, v1, s31, v1 bitop3:0xc
	v_bitop3_b32 v237, v1, s33, v1 bitop3:0xc
	v_bitop3_b32 v238, v1, s34, v1 bitop3:0xc
	v_bitop3_b32 v239, v1, s35, v1 bitop3:0xc
	s_waitcnt lgkmcnt(2)
	v_mfma_f32_32x32x16_bf16 v[96:111], v[124:127], v[136:139], v[96:111]
	ds_read_b128 v[120:123], v200 offset:6144
	ds_read_b128 v[124:127], v200 offset:6656
	v_mul_u32_u24_e32 v236, 0xf00, v236
	v_mul_u32_u24_e32 v237, 0x780, v237
	v_mul_u32_u24_e32 v238, 0x3c0, v238
	v_mul_u32_u24_e32 v239, 0x1e0, v239
	v_bitop3_b32 v224, v14, s31, v14 bitop3:0xc
	v_bitop3_b32 v225, v14, s33, v14 bitop3:0xc
	v_bitop3_b32 v226, v14, s34, v14 bitop3:0xc
	v_bitop3_b32 v227, v14, s35, v14 bitop3:0xc
	s_waitcnt lgkmcnt(3)
	v_mfma_f32_32x32x16_bf16 v[80:95], v[6:9], v[140:143], v[80:95]
	v_mul_u32_u24_e32 v224, 0xf00, v224
	v_mul_u32_u24_e32 v225, 0x780, v225
	v_mul_u32_u24_e32 v226, 0x3c0, v226
	v_mul_u32_u24_e32 v227, 0x1e0, v227
	s_waitcnt lgkmcnt(2)
	v_mfma_f32_32x32x16_bf16 v[96:111], v[10:13], v[140:143], v[96:111]
	s_xor_b64 s[4:5], s[20:21], -1
	s_waitcnt lgkmcnt(1)
	v_mfma_f32_32x32x16_bf16 v[80:95], v[120:123], v[148:151], v[80:95]
	s_waitcnt lgkmcnt(0)
	v_mfma_f32_32x32x16_bf16 v[96:111], v[124:127], v[148:151], v[96:111]
	v_mfma_f32_32x32x16_bf16 v[80:95], v[112:115], v[228:231], v[80:95]
	v_mfma_f32_32x32x16_bf16 v[96:111], v[112:115], v[232:235], v[96:111]
	v_mfma_f32_32x32x16_bf16 v[80:95], v[116:119], v[236:239], v[80:95]
	v_mfma_f32_32x32x16_bf16 v[96:111], v[116:119], v[224:227], v[96:111]
	s_nop 15
	s_nop 7
	v_max3_f32 v1, v80, v81, v82
	v_max3_f32 v6, v83, v84, v85
	v_max3_f32 v1, v1, v86, v87
	v_max3_f32 v6, v6, v88, v89
	v_max3_f32 v1, v1, v90, v91
	v_max3_f32 v6, v6, v92, v93
	v_max3_f32 v1, v1, v94, v95
	v_max_f32 v1, v1, v6
	s_nop 0
	v_max3_f32 v7, v96, v97, v98
	v_max3_f32 v6, v99, v100, v101
	v_max3_f32 v7, v7, v102, v103
	v_max3_f32 v6, v6, v104, v105
	v_max3_f32 v7, v7, v106, v107
	v_max3_f32 v6, v6, v108, v109
	v_max3_f32 v7, v7, v110, v111
	v_max3_f32 v7, v7, v6, v1
	s_nop 0
	v_mov_b32_e32 v1, v7
	s_nop 1
	v_permlane32_swap_b32_e32 v7, v1
	v_max_f32_e32 v1, v7, v1
	v_cmp_lt_f32_e64 s[0:1], s36, v1
	s_and_b64 s[10:11], s[0:1], s[4:5]
	v_cmp_lt_f32_e32 vcc, s37, v1
	s_or_b64 s[4:5], vcc, s[10:11]
	s_and_b64 vcc, exec, s[4:5]
	s_cbranch_vccz .LBB0_3764
	v_cndmask_b32_e64 v6, 0, v1, s[4:5]
	v_exp_f32_e64 v1, -v6
	v_add_f32_e32 v171, v171, v6
	s_or_b64 s[0:1], s[20:21], s[0:1]
	v_xor_b32_e32 v64, 0x80000000, v171
	v_cndmask_b32_e64 v8, v1, 1.0, s[10:11]
	s_andn2_b64 s[4:5], s[20:21], exec
	s_and_b64 s[0:1], s[0:1], exec
	v_pk_add_f32 v[80:81], v[80:81], v[6:7] op_sel_hi:[1,0] neg_lo:[0,1] neg_hi:[0,1]
	v_pk_add_f32 v[96:97], v[96:97], v[6:7] op_sel_hi:[1,0] neg_lo:[0,1] neg_hi:[0,1]
	v_pk_add_f32 v[82:83], v[82:83], v[6:7] op_sel_hi:[1,0] neg_lo:[0,1] neg_hi:[0,1]
	v_pk_add_f32 v[98:99], v[98:99], v[6:7] op_sel_hi:[1,0] neg_lo:[0,1] neg_hi:[0,1]
	v_pk_add_f32 v[84:85], v[84:85], v[6:7] op_sel_hi:[1,0] neg_lo:[0,1] neg_hi:[0,1]
	v_pk_add_f32 v[100:101], v[100:101], v[6:7] op_sel_hi:[1,0] neg_lo:[0,1] neg_hi:[0,1]
	v_pk_add_f32 v[86:87], v[86:87], v[6:7] op_sel_hi:[1,0] neg_lo:[0,1] neg_hi:[0,1]
	v_pk_add_f32 v[102:103], v[102:103], v[6:7] op_sel_hi:[1,0] neg_lo:[0,1] neg_hi:[0,1]
	v_pk_add_f32 v[88:89], v[88:89], v[6:7] op_sel_hi:[1,0] neg_lo:[0,1] neg_hi:[0,1]
	v_pk_add_f32 v[104:105], v[104:105], v[6:7] op_sel_hi:[1,0] neg_lo:[0,1] neg_hi:[0,1]
	v_pk_add_f32 v[90:91], v[90:91], v[6:7] op_sel_hi:[1,0] neg_lo:[0,1] neg_hi:[0,1]
	v_pk_add_f32 v[106:107], v[106:107], v[6:7] op_sel_hi:[1,0] neg_lo:[0,1] neg_hi:[0,1]
	v_pk_add_f32 v[92:93], v[92:93], v[6:7] op_sel_hi:[1,0] neg_lo:[0,1] neg_hi:[0,1]
	v_pk_add_f32 v[108:109], v[108:109], v[6:7] op_sel_hi:[1,0] neg_lo:[0,1] neg_hi:[0,1]
	v_pk_add_f32 v[94:95], v[94:95], v[6:7] op_sel_hi:[1,0] neg_lo:[0,1] neg_hi:[0,1]
	v_pk_add_f32 v[110:111], v[110:111], v[6:7] op_sel_hi:[1,0] neg_lo:[0,1] neg_hi:[0,1]
	v_mov_b32_e32 v65, v64
	v_mov_b32_e32 v66, v64
	v_mov_b32_e32 v67, v64
	v_mov_b32_e32 v68, v64
	v_mov_b32_e32 v69, v64
	v_mov_b32_e32 v70, v64
	v_mov_b32_e32 v71, v64
	v_mov_b32_e32 v72, v64
	v_mov_b32_e32 v73, v64
	v_mov_b32_e32 v74, v64
	v_mov_b32_e32 v75, v64
	v_mov_b32_e32 v76, v64
	v_mov_b32_e32 v77, v64
	v_mov_b32_e32 v78, v64
	v_mov_b32_e32 v79, v64
	v_pk_mul_f32 v[30:31], v[30:31], v[8:9] op_sel_hi:[1,0]
	v_pk_mul_f32 v[28:29], v[28:29], v[8:9] op_sel_hi:[1,0]
	v_pk_mul_f32 v[26:27], v[26:27], v[8:9] op_sel_hi:[1,0]
	v_pk_mul_f32 v[24:25], v[24:25], v[8:9] op_sel_hi:[1,0]
	v_pk_mul_f32 v[22:23], v[22:23], v[8:9] op_sel_hi:[1,0]
	v_pk_mul_f32 v[20:21], v[20:21], v[8:9] op_sel_hi:[1,0]
	v_pk_mul_f32 v[18:19], v[18:19], v[8:9] op_sel_hi:[1,0]
	v_pk_mul_f32 v[16:17], v[16:17], v[8:9] op_sel_hi:[1,0]
	v_pk_mul_f32 v[46:47], v[46:47], v[8:9] op_sel_hi:[1,0]
	v_pk_mul_f32 v[44:45], v[44:45], v[8:9] op_sel_hi:[1,0]
	v_pk_mul_f32 v[42:43], v[42:43], v[8:9] op_sel_hi:[1,0]
	v_pk_mul_f32 v[40:41], v[40:41], v[8:9] op_sel_hi:[1,0]
	v_pk_mul_f32 v[38:39], v[38:39], v[8:9] op_sel_hi:[1,0]
	v_pk_mul_f32 v[36:37], v[36:37], v[8:9] op_sel_hi:[1,0]
	v_pk_mul_f32 v[34:35], v[34:35], v[8:9] op_sel_hi:[1,0]
	v_pk_mul_f32 v[32:33], v[32:33], v[8:9] op_sel_hi:[1,0]
	v_pk_mul_f32 v[62:63], v[62:63], v[8:9] op_sel_hi:[1,0]
	v_pk_mul_f32 v[60:61], v[60:61], v[8:9] op_sel_hi:[1,0]
	v_pk_mul_f32 v[58:59], v[58:59], v[8:9] op_sel_hi:[1,0]
	v_pk_mul_f32 v[56:57], v[56:57], v[8:9] op_sel_hi:[1,0]
	v_pk_mul_f32 v[54:55], v[54:55], v[8:9] op_sel_hi:[1,0]
	v_pk_mul_f32 v[52:53], v[52:53], v[8:9] op_sel_hi:[1,0]
	v_pk_mul_f32 v[50:51], v[50:51], v[8:9] op_sel_hi:[1,0]
	v_pk_mul_f32 v[48:49], v[48:49], v[8:9] op_sel_hi:[1,0]
	s_or_b64 s[20:21], s[4:5], s[0:1]
.LBB0_3764:
	ds_read_b64_tr_b16 v[202:203], v157 offset:8192
	ds_read_b64_tr_b16 v[204:205], v157 offset:8704
	ds_read_b64_tr_b16 v[206:207], v157 offset:12288
	ds_read_b64_tr_b16 v[208:209], v157 offset:12800
	v_exp_f32_e32 v80, v80
	v_exp_f32_e32 v81, v81
	v_exp_f32_e32 v82, v82
	v_exp_f32_e32 v83, v83
	v_exp_f32_e32 v84, v84
	v_exp_f32_e32 v85, v85
	v_exp_f32_e32 v86, v86
	v_exp_f32_e32 v87, v87
	v_cvt_pk_bf16_f32 v6, v80, v81
	v_cvt_pk_bf16_f32 v7, v82, v83
	v_cvt_pk_bf16_f32 v8, v84, v85
	v_cvt_pk_bf16_f32 v9, v86, v87
	ds_read_b64_tr_b16 v[210:211], v157 offset:9216
	ds_read_b64_tr_b16 v[212:213], v157 offset:9728
	ds_read_b64_tr_b16 v[214:215], v157 offset:13312
	ds_read_b64_tr_b16 v[216:217], v157 offset:13824
	s_waitcnt lgkmcnt(4)
	v_mfma_f32_32x32x16_bf16 v[16:31], v[202:205], v[6:9], v[16:31]
	v_exp_f32_e32 v88, v88
	v_exp_f32_e32 v89, v89
	v_exp_f32_e32 v90, v90
	v_mfma_f32_32x32x16_bf16 v[32:47], v[206:209], v[6:9], v[32:47]
	v_exp_f32_e32 v91, v91
	v_exp_f32_e32 v92, v92
	v_exp_f32_e32 v93, v93
	v_mfma_f32_32x32x16_bf16 v[48:63], v[128:131], v[6:9], v[48:63]
	v_exp_f32_e32 v94, v94
	v_exp_f32_e32 v95, v95
	v_cvt_pk_bf16_f32 v10, v88, v89
	v_cvt_pk_bf16_f32 v11, v90, v91
	v_cvt_pk_bf16_f32 v12, v92, v93
	v_cvt_pk_bf16_f32 v13, v94, v95
	ds_read_b64_tr_b16 v[202:203], v157 offset:10240
	ds_read_b64_tr_b16 v[204:205], v157 offset:10752
	ds_read_b64_tr_b16 v[206:207], v157 offset:14336
	ds_read_b64_tr_b16 v[208:209], v157 offset:14848
	s_waitcnt lgkmcnt(4)
	v_mfma_f32_32x32x16_bf16 v[16:31], v[210:213], v[10:13], v[16:31]
	v_exp_f32_e32 v96, v96
	v_exp_f32_e32 v97, v97
	v_exp_f32_e32 v98, v98
	v_mfma_f32_32x32x16_bf16 v[32:47], v[214:217], v[10:13], v[32:47]
	v_exp_f32_e32 v99, v99
	v_exp_f32_e32 v100, v100
	v_exp_f32_e32 v101, v101
	v_mfma_f32_32x32x16_bf16 v[48:63], v[128:131], v[10:13], v[48:63]
	v_exp_f32_e32 v102, v102
	v_exp_f32_e32 v103, v103
	v_cvt_pk_bf16_f32 v228, v96, v97
	v_cvt_pk_bf16_f32 v229, v98, v99
	v_cvt_pk_bf16_f32 v230, v100, v101
	v_cvt_pk_bf16_f32 v231, v102, v103
	ds_read_b64_tr_b16 v[210:211], v157 offset:11264
	ds_read_b64_tr_b16 v[212:213], v157 offset:11776
	ds_read_b64_tr_b16 v[214:215], v157 offset:15360
	ds_read_b64_tr_b16 v[216:217], v157 offset:15872
	s_waitcnt lgkmcnt(4)
	v_mfma_f32_32x32x16_bf16 v[16:31], v[202:205], v[228:231], v[16:31]
	v_exp_f32_e32 v104, v104
	v_exp_f32_e32 v105, v105
	v_exp_f32_e32 v106, v106
	v_mfma_f32_32x32x16_bf16 v[32:47], v[206:209], v[228:231], v[32:47]
	v_exp_f32_e32 v107, v107
	v_exp_f32_e32 v108, v108
	v_exp_f32_e32 v109, v109
	v_mfma_f32_32x32x16_bf16 v[48:63], v[128:131], v[228:231], v[48:63]
	v_exp_f32_e32 v110, v110
	v_exp_f32_e32 v111, v111
	v_cvt_pk_bf16_f32 v232, v104, v105
	v_cvt_pk_bf16_f32 v233, v106, v107
	v_cvt_pk_bf16_f32 v234, v108, v109
	v_cvt_pk_bf16_f32 v235, v110, v111
	s_waitcnt lgkmcnt(0)
	s_nop 0
	v_mfma_f32_32x32x16_bf16 v[16:31], v[210:213], v[232:235], v[16:31]
	v_mfma_f32_32x32x16_bf16 v[32:47], v[214:217], v[232:235], v[32:47]
	v_mfma_f32_32x32x16_bf16 v[48:63], v[128:131], v[232:235], v[48:63]
; __device__ __forceinline__ float max32raw(const f32x16& a, const f32x16& b) {
;     float x, y;
;     asm volatile("s_nop 15\n\ts_nop 7\n\t"
;         "v_max3_f32 %0, %2, %3, %4\n\tv_max3_f32 %1, %5, %6, %7\n\t"
;         "v_max3_f32 %0, %0, %8, %9\n\tv_max3_f32 %1, %1, %10, %11\n\t"
;         "v_max3_f32 %0, %0, %12, %13\n\tv_max3_f32 %1, %1, %14, %15\n\t"
;         "v_max3_f32 %0, %0, %16, %17\n\tv_max_f32 %0, %0, %1"
;         : "=&v"(x), "=&v"(y)
;         : "v"(a[0]), "v"(a[1]), "v"(a[2]), "v"(a[3]), "v"(a[4]), "v"(a[5]), "v"(a[6]), "v"(a[7]), "v"(a[8]), "v"(a[9]), "v"(a[10]), "v"(a[11]), "v"(a[12]), "v"(a[13]), "v"(a[14]), "v"(a[15]));
;     float u, v;
;     asm volatile("v_max3_f32 %0, %2, %3, %4\n\tv_max3_f32 %1, %5, %6, %7\n\t"
;         "v_max3_f32 %0, %0, %8, %9\n\tv_max3_f32 %1, %1, %10, %11\n\t"
;         "v_max3_f32 %0, %0, %12, %13\n\tv_max3_f32 %1, %1, %14, %15\n\t"
;         "v_max3_f32 %0, %0, %16, %17\n\tv_max3_f32 %0, %0, %1, %18"
;         : "=&v"(u), "=&v"(v)
;         : "v"(b[0]), "v"(b[1]), "v"(b[2]), "v"(b[3]), "v"(b[4]), "v"(b[5]), "v"(b[6]), "v"(b[7]), "v"(b[8]), "v"(b[9]), "v"(b[10]), "v"(b[11]), "v"(b[12]), "v"(b[13]), "v"(b[14]), "v"(b[15]), "v"(x));
;     return u;
; }
.LBB0_3765:
	s_cmp_ge_u32 s51, s47
	s_cbranch_scc1 .LBB0_3770
	ds_read_b128 v[6:9], v200 offset:16384
	ds_read_b128 v[10:13], v200 offset:16896
	ds_read_b128 v[120:123], v200 offset:18432
	ds_read_b128 v[124:127], v200 offset:18944
	v_lshrrev_b32_e32 v1, v160, v154
	v_lshrrev_b32_e32 v14, v160, v155
	v_bitop3_b32 v228, v1, s27, v1 bitop3:0xc
	v_bitop3_b32 v229, v1, s28, v1 bitop3:0xc
	v_bitop3_b32 v230, v1, s29, v1 bitop3:0xc
	v_bitop3_b32 v231, v1, s30, v1 bitop3:0xc
	s_waitcnt lgkmcnt(3)
	v_mfma_f32_32x32x16_bf16 v[80:95], v[6:9], v[144:147], v[64:79]
	v_mul_u32_u24_e32 v228, 0xf000, v228
	v_mul_u32_u24_e32 v229, 0x7800, v229
	v_mul_u32_u24_e32 v230, 0x3c00, v230
	v_mul_u32_u24_e32 v231, 0x1e00, v231
	s_waitcnt lgkmcnt(2)
	v_mfma_f32_32x32x16_bf16 v[96:111], v[10:13], v[144:147], v[64:79]
	ds_read_b128 v[6:9], v200 offset:20480
	ds_read_b128 v[10:13], v200 offset:20992
	v_bitop3_b32 v232, v14, s27, v14 bitop3:0xc
	v_bitop3_b32 v233, v14, s28, v14 bitop3:0xc
	v_bitop3_b32 v234, v14, s29, v14 bitop3:0xc
	v_bitop3_b32 v235, v14, s30, v14 bitop3:0xc
	v_mul_u32_u24_e32 v232, 0xf000, v232
	v_mul_u32_u24_e32 v233, 0x7800, v233
	v_mul_u32_u24_e32 v234, 0x3c00, v234
	v_mul_u32_u24_e32 v235, 0x1e00, v235
	s_waitcnt lgkmcnt(3)
	v_mfma_f32_32x32x16_bf16 v[80:95], v[120:123], v[136:139], v[80:95]
	v_bitop3_b32 v236, v1, s31, v1 bitop3:0xc
	v_bitop3_b32 v237, v1, s33, v1 bitop3:0xc
	v_bitop3_b32 v238, v1, s34, v1 bitop3:0xc
	v_bitop3_b32 v239, v1, s35, v1 bitop3:0xc
	s_waitcnt lgkmcnt(2)
	v_mfma_f32_32x32x16_bf16 v[96:111], v[124:127], v[136:139], v[96:111]
	ds_read_b128 v[120:123], v200 offset:22528
	ds_read_b128 v[124:127], v200 offset:23040
	v_mul_u32_u24_e32 v236, 0xf00, v236
	v_mul_u32_u24_e32 v237, 0x780, v237
	v_mul_u32_u24_e32 v238, 0x3c0, v238
	v_mul_u32_u24_e32 v239, 0x1e0, v239
	v_bitop3_b32 v224, v14, s31, v14 bitop3:0xc
	v_bitop3_b32 v225, v14, s33, v14 bitop3:0xc
	v_bitop3_b32 v226, v14, s34, v14 bitop3:0xc
	v_bitop3_b32 v227, v14, s35, v14 bitop3:0xc
	s_waitcnt lgkmcnt(3)
	v_mfma_f32_32x32x16_bf16 v[80:95], v[6:9], v[140:143], v[80:95]
	v_mul_u32_u24_e32 v224, 0xf00, v224
	v_mul_u32_u24_e32 v225, 0x780, v225
	v_mul_u32_u24_e32 v226, 0x3c0, v226
	v_mul_u32_u24_e32 v227, 0x1e0, v227
	s_waitcnt lgkmcnt(2)
	v_mfma_f32_32x32x16_bf16 v[96:111], v[10:13], v[140:143], v[96:111]
	s_xor_b64 s[4:5], s[20:21], -1
	s_and_b64 vcc, exec, s[4:5]
	s_waitcnt lgkmcnt(1)
	v_mfma_f32_32x32x16_bf16 v[80:95], v[120:123], v[148:151], v[80:95]
	s_waitcnt lgkmcnt(0)
	v_mfma_f32_32x32x16_bf16 v[96:111], v[124:127], v[148:151], v[96:111]
	v_mfma_f32_32x32x16_bf16 v[80:95], v[112:115], v[228:231], v[80:95]
	v_mfma_f32_32x32x16_bf16 v[96:111], v[112:115], v[232:235], v[96:111]
	v_mfma_f32_32x32x16_bf16 v[80:95], v[116:119], v[236:239], v[80:95]
	v_mfma_f32_32x32x16_bf16 v[96:111], v[116:119], v[224:227], v[96:111]
	s_cbranch_vccz .LBB0_3769
	s_nop 15
	s_nop 7
	v_max3_f32 v1, v80, v81, v82
	v_max3_f32 v6, v83, v84, v85
	v_max3_f32 v1, v1, v86, v87
	v_max3_f32 v6, v6, v88, v89
	v_max3_f32 v1, v1, v90, v91
	v_max3_f32 v6, v6, v92, v93
	v_max3_f32 v1, v1, v94, v95
	v_max_f32 v1, v1, v6
	s_nop 0
	v_max3_f32 v7, v96, v97, v98
	v_max3_f32 v6, v99, v100, v101
	v_max3_f32 v7, v7, v102, v103
	v_max3_f32 v6, v6, v104, v105
	v_max3_f32 v7, v7, v106, v107
	v_max3_f32 v6, v6, v108, v109
	v_max3_f32 v7, v7, v110, v111
	v_max3_f32 v7, v7, v6, v1
	s_nop 0
	v_mov_b32_e32 v1, v7
	s_nop 1
	v_permlane32_swap_b32_e32 v7, v1
	v_max_f32_e32 v1, v7, v1
	v_cmp_lt_f32_e64 s[0:1], s36, v1
	s_and_b64 s[10:11], s[0:1], s[4:5]
	v_cmp_lt_f32_e32 vcc, s37, v1
	s_or_b64 s[4:5], vcc, s[10:11]
	s_and_b64 vcc, exec, s[4:5]
	s_cbranch_vccz .LBB0_3769
	v_cndmask_b32_e64 v1, 0, v1, s[4:5]
	v_exp_f32_e64 v6, -v1
	v_add_f32_e32 v171, v171, v1
	s_or_b64 s[0:1], s[20:21], s[0:1]
	v_xor_b32_e32 v64, 0x80000000, v171
	v_cndmask_b32_e64 v6, v6, 1.0, s[10:11]
	s_andn2_b64 s[4:5], s[20:21], exec
	s_and_b64 s[0:1], s[0:1], exec
	v_mov_b32_e32 v65, v64
	v_mov_b32_e32 v66, v64
	v_mov_b32_e32 v67, v64
	v_mov_b32_e32 v68, v64
	v_mov_b32_e32 v69, v64
	v_mov_b32_e32 v70, v64
	v_mov_b32_e32 v71, v64
	v_mov_b32_e32 v72, v64
	v_mov_b32_e32 v73, v64
	v_mov_b32_e32 v74, v64
	v_mov_b32_e32 v75, v64
	v_mov_b32_e32 v76, v64
	v_mov_b32_e32 v77, v64
	v_mov_b32_e32 v78, v64
	v_mov_b32_e32 v79, v64
	v_pk_mul_f32 v[30:31], v[30:31], v[6:7] op_sel_hi:[1,0]
	v_pk_mul_f32 v[28:29], v[28:29], v[6:7] op_sel_hi:[1,0]
	v_pk_mul_f32 v[26:27], v[26:27], v[6:7] op_sel_hi:[1,0]
	v_pk_mul_f32 v[24:25], v[24:25], v[6:7] op_sel_hi:[1,0]
	v_pk_mul_f32 v[22:23], v[22:23], v[6:7] op_sel_hi:[1,0]
	v_pk_mul_f32 v[20:21], v[20:21], v[6:7] op_sel_hi:[1,0]
	v_pk_mul_f32 v[18:19], v[18:19], v[6:7] op_sel_hi:[1,0]
	v_pk_mul_f32 v[16:17], v[16:17], v[6:7] op_sel_hi:[1,0]
	v_pk_mul_f32 v[46:47], v[46:47], v[6:7] op_sel_hi:[1,0]
	v_pk_mul_f32 v[44:45], v[44:45], v[6:7] op_sel_hi:[1,0]
	v_pk_mul_f32 v[42:43], v[42:43], v[6:7] op_sel_hi:[1,0]
	v_pk_mul_f32 v[40:41], v[40:41], v[6:7] op_sel_hi:[1,0]
	v_pk_mul_f32 v[38:39], v[38:39], v[6:7] op_sel_hi:[1,0]
	v_pk_mul_f32 v[36:37], v[36:37], v[6:7] op_sel_hi:[1,0]
	v_pk_mul_f32 v[34:35], v[34:35], v[6:7] op_sel_hi:[1,0]
	v_pk_mul_f32 v[32:33], v[32:33], v[6:7] op_sel_hi:[1,0]
	v_pk_mul_f32 v[62:63], v[62:63], v[6:7] op_sel_hi:[1,0]
	v_pk_mul_f32 v[60:61], v[60:61], v[6:7] op_sel_hi:[1,0]
	v_pk_mul_f32 v[58:59], v[58:59], v[6:7] op_sel_hi:[1,0]
	v_pk_mul_f32 v[56:57], v[56:57], v[6:7] op_sel_hi:[1,0]
	v_pk_mul_f32 v[54:55], v[54:55], v[6:7] op_sel_hi:[1,0]
	v_pk_mul_f32 v[52:53], v[52:53], v[6:7] op_sel_hi:[1,0]
	v_pk_mul_f32 v[50:51], v[50:51], v[6:7] op_sel_hi:[1,0]
	v_pk_mul_f32 v[48:49], v[48:49], v[6:7] op_sel_hi:[1,0]
	v_sub_f32_e32 v95, v95, v1
	v_sub_f32_e32 v94, v94, v1
	v_sub_f32_e32 v93, v93, v1
	v_sub_f32_e32 v92, v92, v1
	v_sub_f32_e32 v91, v91, v1
	v_sub_f32_e32 v90, v90, v1
	v_sub_f32_e32 v89, v89, v1
	v_sub_f32_e32 v88, v88, v1
	v_sub_f32_e32 v87, v87, v1
	v_sub_f32_e32 v86, v86, v1
	v_sub_f32_e32 v85, v85, v1
	v_sub_f32_e32 v84, v84, v1
	v_sub_f32_e32 v83, v83, v1
	v_sub_f32_e32 v82, v82, v1
	v_sub_f32_e32 v81, v81, v1
	v_sub_f32_e32 v80, v80, v1
	v_sub_f32_e32 v111, v111, v1
	v_sub_f32_e32 v110, v110, v1
	v_sub_f32_e32 v109, v109, v1
	v_sub_f32_e32 v108, v108, v1
	v_sub_f32_e32 v107, v107, v1
	v_sub_f32_e32 v106, v106, v1
	v_sub_f32_e32 v105, v105, v1
	v_sub_f32_e32 v104, v104, v1
	v_sub_f32_e32 v103, v103, v1
	v_sub_f32_e32 v102, v102, v1
	v_sub_f32_e32 v101, v101, v1
	v_sub_f32_e32 v100, v100, v1
	v_sub_f32_e32 v99, v99, v1
	v_sub_f32_e32 v98, v98, v1
	v_sub_f32_e32 v97, v97, v1
	v_sub_f32_e32 v96, v96, v1
	s_or_b64 s[20:21], s[4:5], s[0:1]
.LBB0_3769:
	s_nop 8
	ds_read_b64_tr_b16 v[202:203], v157 offset:24576
	ds_read_b64_tr_b16 v[204:205], v157 offset:25088
	ds_read_b64_tr_b16 v[206:207], v157 offset:28672
	ds_read_b64_tr_b16 v[208:209], v157 offset:29184
	v_exp_f32_e32 v80, v80
	v_exp_f32_e32 v81, v81
	v_exp_f32_e32 v82, v82
	v_exp_f32_e32 v83, v83
	v_exp_f32_e32 v84, v84
	v_exp_f32_e32 v85, v85
	v_exp_f32_e32 v86, v86
	v_exp_f32_e32 v87, v87
	v_cvt_pk_bf16_f32 v6, v80, v81
	v_cvt_pk_bf16_f32 v7, v82, v83
	v_cvt_pk_bf16_f32 v8, v84, v85
	v_cvt_pk_bf16_f32 v9, v86, v87
	ds_read_b64_tr_b16 v[210:211], v157 offset:25600
	ds_read_b64_tr_b16 v[212:213], v157 offset:26112
	ds_read_b64_tr_b16 v[214:215], v157 offset:29696
	ds_read_b64_tr_b16 v[216:217], v157 offset:30208
	s_waitcnt lgkmcnt(4)
	v_mfma_f32_32x32x16_bf16 v[16:31], v[202:205], v[6:9], v[16:31]
	v_exp_f32_e32 v88, v88
	v_exp_f32_e32 v89, v89
	v_exp_f32_e32 v90, v90
	v_mfma_f32_32x32x16_bf16 v[32:47], v[206:209], v[6:9], v[32:47]
	v_exp_f32_e32 v91, v91
	v_exp_f32_e32 v92, v92
	v_exp_f32_e32 v93, v93
	v_mfma_f32_32x32x16_bf16 v[48:63], v[128:131], v[6:9], v[48:63]
	v_exp_f32_e32 v94, v94
	v_exp_f32_e32 v95, v95
	v_cvt_pk_bf16_f32 v10, v88, v89
	v_cvt_pk_bf16_f32 v11, v90, v91
	v_cvt_pk_bf16_f32 v12, v92, v93
	v_cvt_pk_bf16_f32 v13, v94, v95
	ds_read_b64_tr_b16 v[202:203], v157 offset:26624
	ds_read_b64_tr_b16 v[204:205], v157 offset:27136
	ds_read_b64_tr_b16 v[206:207], v157 offset:30720
	ds_read_b64_tr_b16 v[208:209], v157 offset:31232
	s_waitcnt lgkmcnt(4)
	v_mfma_f32_32x32x16_bf16 v[16:31], v[210:213], v[10:13], v[16:31]
	v_exp_f32_e32 v96, v96
	v_exp_f32_e32 v97, v97
	v_exp_f32_e32 v98, v98
	v_mfma_f32_32x32x16_bf16 v[32:47], v[214:217], v[10:13], v[32:47]
	v_exp_f32_e32 v99, v99
	v_exp_f32_e32 v100, v100
	v_exp_f32_e32 v101, v101
	v_mfma_f32_32x32x16_bf16 v[48:63], v[128:131], v[10:13], v[48:63]
	v_exp_f32_e32 v102, v102
	v_exp_f32_e32 v103, v103
	v_cvt_pk_bf16_f32 v228, v96, v97
	v_cvt_pk_bf16_f32 v229, v98, v99
	v_cvt_pk_bf16_f32 v230, v100, v101
	v_cvt_pk_bf16_f32 v231, v102, v103
	ds_read_b64_tr_b16 v[210:211], v157 offset:27648
	ds_read_b64_tr_b16 v[212:213], v157 offset:28160
	ds_read_b64_tr_b16 v[214:215], v157 offset:31744
	ds_read_b64_tr_b16 v[216:217], v157 offset:32256
	s_waitcnt lgkmcnt(4)
	v_mfma_f32_32x32x16_bf16 v[16:31], v[202:205], v[228:231], v[16:31]
	v_exp_f32_e32 v104, v104
	v_exp_f32_e32 v105, v105
	v_exp_f32_e32 v106, v106
	v_mfma_f32_32x32x16_bf16 v[32:47], v[206:209], v[228:231], v[32:47]
	v_exp_f32_e32 v107, v107
	v_exp_f32_e32 v108, v108
	v_exp_f32_e32 v109, v109
	v_mfma_f32_32x32x16_bf16 v[48:63], v[128:131], v[228:231], v[48:63]
	v_exp_f32_e32 v110, v110
	v_exp_f32_e32 v111, v111
	v_cvt_pk_bf16_f32 v232, v104, v105
	v_cvt_pk_bf16_f32 v233, v106, v107
	v_cvt_pk_bf16_f32 v234, v108, v109
	v_cvt_pk_bf16_f32 v235, v110, v111
	s_waitcnt lgkmcnt(0)
	s_nop 0
	v_mfma_f32_32x32x16_bf16 v[16:31], v[210:213], v[232:235], v[16:31]
	v_mfma_f32_32x32x16_bf16 v[32:47], v[214:217], v[232:235], v[32:47]
	v_mfma_f32_32x32x16_bf16 v[48:63], v[128:131], v[232:235], v[48:63]
